# phase_mod k-loop: next 16-row batch of ada_w loads issued before the current batch is consumed (depth-1 software pipeline, counted waits dropped)
# speedup vs baseline: 1.0062x; 1.0017x over previous
; __device__ __forceinline__ void phase_mod(const float* c, const float* ada_w, const float* ada_b, float* mod, unsigned char* ldsb) {
;     ...
;     for (int item = bid; item < 288; item += gridDim.x) {
;         const int l = item / 144, n0 = (item % 144) * 64;
;         const float* W = ada_w + (unsigned)l * 1024 * 9216 + n0 + lane;
;         float acc[8];
; #pragma unroll
;         for (int b = 0; b < 8; ++b) acc[b] = 0.f;
;         const int k0 = w * 128;
; #pragma unroll 16
;         for (int k = k0; k < k0 + 128; ++k) {
;             const float wv = W[(unsigned)k * 9216];
; #pragma unroll
;             for (int b = 0; b < 8; ++b) acc[b] += cact[b * 1024 + k] * wv;
;         }
.LBB0_8:
	s_mul_hi_i32 s6, s3, 0x38e38e39
	s_lshr_b32 s8, s6, 31
	s_ashr_i32 s76, s6, 5
	s_add_i32 s76, s76, s8
	s_mul_i32 s6, s76, 0x90
	s_sub_i32 s6, s3, s6
	s_lshl_b32 s8, s6, 6
	s_mul_i32 s6, s76, 0x900000
	s_lshl_b64 s[10:11], s[6:7], 2
	s_add_u32 s6, s60, s10
	s_addc_u32 s12, s61, s11
	s_ashr_i32 s9, s8, 31
	s_lshl_b64 s[10:11], s[8:9], 2
	s_add_u32 s10, s6, s10
	s_addc_u32 s11, s12, s11
	v_lshl_add_u64 v[8:9], s[10:11], 0, v[6:7]
	s_mov_b32 s9, s73
	s_mov_b32 s77, s7
	v_mov_b32_e32 v10, 0
	v_mov_b32_e32 v11, v5
	v_mov_b32_e32 v12, 0
	v_mov_b32_e32 v13, v5
	v_mov_b32_e32 v14, 0
	v_mov_b32_e32 v15, v5
	v_mov_b32_e32 v16, 0
	v_mov_b32_e32 v17, v5
	s_add_i32 s6, s75, s77
	v_lshl_add_u64 v[220:221], s[6:7], 2, v[8:9]
	s_mov_b32 s11, s7
	s_mov_b32 s13, s7
	s_mov_b32 s15, s7
	s_mov_b32 s17, s7
	s_mov_b32 s19, s7
	s_mov_b32 s21, s7
	s_mov_b32 s23, s7
	s_mov_b32 s25, s7
	s_mov_b32 s27, s7
	s_mov_b32 s29, s7
	s_mov_b32 s31, s7
	s_mov_b32 s55, s7
	s_mov_b32 s69, s7
	s_mov_b32 s71, s7
	s_add_i32 s10, s6, 0x2400
	s_add_i32 s12, s6, 0x4800
	s_add_i32 s14, s6, 0x6c00
	s_add_i32 s16, s6, 0x9000
	s_add_i32 s18, s6, 0xb400
	s_add_i32 s20, s6, 0xd800
	s_add_i32 s22, s6, 0xfc00
	s_add_i32 s24, s6, 0x12000
	s_add_i32 s26, s6, 0x14400
	s_add_i32 s28, s6, 0x16800
	s_add_i32 s30, s6, 0x18c00
	s_add_i32 s54, s6, 0x1b000
	s_add_i32 s68, s6, 0x1d400
	s_add_i32 s70, s6, 0x1f800
	s_add_i32 s6, s6, 0x21c00
	v_lshl_add_u64 v[222:223], s[10:11], 2, v[8:9]
	v_lshl_add_u64 v[224:225], s[12:13], 2, v[8:9]
	v_lshl_add_u64 v[226:227], s[14:15], 2, v[8:9]
	v_lshl_add_u64 v[228:229], s[16:17], 2, v[8:9]
	v_lshl_add_u64 v[230:231], s[18:19], 2, v[8:9]
	v_lshl_add_u64 v[232:233], s[20:21], 2, v[8:9]
	v_lshl_add_u64 v[234:235], s[22:23], 2, v[8:9]
	v_lshl_add_u64 v[236:237], s[24:25], 2, v[8:9]
	v_lshl_add_u64 v[238:239], s[26:27], 2, v[8:9]
	v_lshl_add_u64 v[240:241], s[28:29], 2, v[8:9]
	v_lshl_add_u64 v[242:243], s[30:31], 2, v[8:9]
	v_lshl_add_u64 v[244:245], s[54:55], 2, v[8:9]
	v_lshl_add_u64 v[246:247], s[68:69], 2, v[8:9]
	v_lshl_add_u64 v[248:249], s[70:71], 2, v[8:9]
	v_lshl_add_u64 v[250:251], s[6:7], 2, v[8:9]
	global_load_dword v204, v[220:221], off
	global_load_dword v205, v[222:223], off
	global_load_dword v206, v[224:225], off
	global_load_dword v207, v[226:227], off
	global_load_dword v208, v[228:229], off
	global_load_dword v209, v[230:231], off
	global_load_dword v210, v[232:233], off
	global_load_dword v211, v[234:235], off
	global_load_dword v212, v[236:237], off
	global_load_dword v213, v[238:239], off
	global_load_dword v214, v[240:241], off
	global_load_dword v215, v[242:243], off
	global_load_dword v216, v[244:245], off
	global_load_dword v217, v[246:247], off
	global_load_dword v218, v[248:249], off
	global_load_dword v219, v[250:251], off
.LBB0_9:
	v_mov_b32_e32 v4, s9
	ds_read_b128 v[18:21], v4
	ds_read_b128 v[22:25], v4 offset:16
	ds_read_b128 v[26:29], v4 offset:4096
	ds_read_b128 v[30:33], v4 offset:4112
	ds_read_b128 v[34:37], v4 offset:8192
	ds_read_b128 v[38:41], v4 offset:8208
	ds_read_b128 v[42:45], v4 offset:12288
	ds_read_b128 v[46:49], v4 offset:12304
	ds_read_b128 v[50:53], v4 offset:16384
	ds_read_b128 v[54:57], v4 offset:16400
	ds_read_b128 v[58:61], v4 offset:20480
	ds_read_b128 v[62:65], v4 offset:20496
	ds_read_b128 v[66:69], v4 offset:24576
	ds_read_b128 v[70:73], v4 offset:24592
	ds_read_b128 v[74:77], v4 offset:28672
	ds_read_b128 v[78:81], v4 offset:28688
	ds_read_b128 v[82:85], v4 offset:32
	ds_read_b128 v[86:89], v4 offset:48
	ds_read_b128 v[90:93], v4 offset:4128
	ds_read_b128 v[94:97], v4 offset:4144
	ds_read_b128 v[98:101], v4 offset:8224
	ds_read_b128 v[102:105], v4 offset:8240
	ds_read_b128 v[106:109], v4 offset:12320
	ds_read_b128 v[110:113], v4 offset:12336
	ds_read_b128 v[114:117], v4 offset:16416
	ds_read_b128 v[118:121], v4 offset:16432
	ds_read_b128 v[122:125], v4 offset:20512
	ds_read_b128 v[126:129], v4 offset:20528
	ds_read_b128 v[130:133], v4 offset:24608
	ds_read_b128 v[134:137], v4 offset:24624
	ds_read_b128 v[138:141], v4 offset:28704
	ds_read_b128 v[142:145], v4 offset:28720
	s_waitcnt vmcnt(0)
	v_mov_b32_e32 v4, v204
	v_mov_b32_e32 v146, v205
	v_mov_b32_e32 v148, v206
	v_mov_b32_e32 v150, v207
	v_mov_b32_e32 v152, v208
	v_mov_b32_e32 v154, v209
	v_mov_b32_e32 v156, v210
	v_mov_b32_e32 v158, v211
	v_mov_b32_e32 v160, v212
	v_mov_b32_e32 v162, v213
	v_mov_b32_e32 v164, v214
	v_mov_b32_e32 v166, v215
	v_mov_b32_e32 v168, v216
	v_mov_b32_e32 v170, v217
	v_mov_b32_e32 v172, v218
	v_mov_b32_e32 v174, v219
	s_cmp_eq_u32 s77, 0xfc000
	s_cbranch_scc1 .Lmod_nopf
	s_add_i32 s6, s75, s77
	s_add_i32 s6, s6, 0x24000
	v_lshl_add_u64 v[220:221], s[6:7], 2, v[8:9]
	s_mov_b32 s11, s7
	s_mov_b32 s13, s7
	s_mov_b32 s15, s7
	s_mov_b32 s17, s7
	s_mov_b32 s19, s7
	s_mov_b32 s21, s7
	s_mov_b32 s23, s7
	s_mov_b32 s25, s7
	s_mov_b32 s27, s7
	s_mov_b32 s29, s7
	s_mov_b32 s31, s7
	s_mov_b32 s55, s7
	s_mov_b32 s69, s7
	s_mov_b32 s71, s7
	s_add_i32 s10, s6, 0x2400
	s_add_i32 s12, s6, 0x4800
	s_add_i32 s14, s6, 0x6c00
	s_add_i32 s16, s6, 0x9000
	s_add_i32 s18, s6, 0xb400
	s_add_i32 s20, s6, 0xd800
	s_add_i32 s22, s6, 0xfc00
	s_add_i32 s24, s6, 0x12000
	s_add_i32 s26, s6, 0x14400
	s_add_i32 s28, s6, 0x16800
	s_add_i32 s30, s6, 0x18c00
	s_add_i32 s54, s6, 0x1b000
	s_add_i32 s68, s6, 0x1d400
	s_add_i32 s70, s6, 0x1f800
	s_add_i32 s6, s6, 0x21c00
	v_lshl_add_u64 v[222:223], s[10:11], 2, v[8:9]
	v_lshl_add_u64 v[224:225], s[12:13], 2, v[8:9]
	v_lshl_add_u64 v[226:227], s[14:15], 2, v[8:9]
	v_lshl_add_u64 v[228:229], s[16:17], 2, v[8:9]
	v_lshl_add_u64 v[230:231], s[18:19], 2, v[8:9]
	v_lshl_add_u64 v[232:233], s[20:21], 2, v[8:9]
	v_lshl_add_u64 v[234:235], s[22:23], 2, v[8:9]
	v_lshl_add_u64 v[236:237], s[24:25], 2, v[8:9]
	v_lshl_add_u64 v[238:239], s[26:27], 2, v[8:9]
	v_lshl_add_u64 v[240:241], s[28:29], 2, v[8:9]
	v_lshl_add_u64 v[242:243], s[30:31], 2, v[8:9]
	v_lshl_add_u64 v[244:245], s[54:55], 2, v[8:9]
	v_lshl_add_u64 v[246:247], s[68:69], 2, v[8:9]
	v_lshl_add_u64 v[248:249], s[70:71], 2, v[8:9]
	v_lshl_add_u64 v[250:251], s[6:7], 2, v[8:9]
	global_load_dword v204, v[220:221], off
	global_load_dword v205, v[222:223], off
	global_load_dword v206, v[224:225], off
	global_load_dword v207, v[226:227], off
	global_load_dword v208, v[228:229], off
	global_load_dword v209, v[230:231], off
	global_load_dword v210, v[232:233], off
	global_load_dword v211, v[234:235], off
	global_load_dword v212, v[236:237], off
	global_load_dword v213, v[238:239], off
	global_load_dword v214, v[240:241], off
	global_load_dword v215, v[242:243], off
	global_load_dword v216, v[244:245], off
	global_load_dword v217, v[246:247], off
	global_load_dword v218, v[248:249], off
	global_load_dword v219, v[250:251], off
; __device__ __forceinline__ void phase_mod(const float* c, const float* ada_w, const float* ada_b, float* mod, unsigned char* ldsb) {
;     ...
; #pragma unroll 16
;         for (int k = k0; k < k0 + 128; ++k) {
;             const float wv = W[(unsigned)k * 9216];
; #pragma unroll
;             for (int b = 0; b < 8; ++b) acc[b] += cact[b * 1024 + k] * wv;
;         }
.Lmod_nopf:
	s_waitcnt lgkmcnt(0)
	v_mov_b32_e32 v176, v18
	v_mov_b32_e32 v177, v26
	v_mov_b32_e32 v26, v19
	v_mov_b32_e32 v18, v20
	v_mov_b32_e32 v19, v28
	v_mov_b32_e32 v28, v21
	v_mov_b32_e32 v20, v34
	v_mov_b32_e32 v21, v42
	v_mov_b32_e32 v42, v35
	v_mov_b32_e32 v34, v36
	v_mov_b32_e32 v35, v44
	v_mov_b32_e32 v44, v37
	v_mov_b32_e32 v36, v50
	v_mov_b32_e32 v37, v58
	v_mov_b32_e32 v58, v51
	v_mov_b32_e32 v50, v52
	v_mov_b32_e32 v51, v60
	v_mov_b32_e32 v60, v53
	v_mov_b32_e32 v52, v66
	v_mov_b32_e32 v53, v74
	v_mov_b32_e32 v74, v67
	v_mov_b32_e32 v66, v68
	v_mov_b32_e32 v67, v76
	v_mov_b32_e32 v76, v69
	v_mov_b32_e32 v68, v22
	v_mov_b32_e32 v69, v30
	v_mov_b32_e32 v30, v23
	v_mov_b32_e32 v22, v24
	v_mov_b32_e32 v23, v32
	v_mov_b32_e32 v32, v25
	v_mov_b32_e32 v24, v38
	v_mov_b32_e32 v25, v46
	v_mov_b32_e32 v46, v39
	v_mov_b32_e32 v38, v40
	v_pk_fma_f32 v[12:13], v[4:5], v[176:177], v[12:13] op_sel_hi:[0,1,1]
	v_pk_fma_f32 v[14:15], v[4:5], v[20:21], v[14:15] op_sel_hi:[0,1,1]
	v_pk_fma_f32 v[16:17], v[4:5], v[36:37], v[16:17] op_sel_hi:[0,1,1]
	v_pk_fma_f32 v[10:11], v[4:5], v[52:53], v[10:11] op_sel_hi:[0,1,1]
	v_mov_b32_e32 v39, v48
	v_mov_b32_e32 v48, v41
	v_mov_b32_e32 v40, v54
	v_mov_b32_e32 v41, v62
	v_mov_b32_e32 v62, v55
	v_mov_b32_e32 v54, v56
	v_mov_b32_e32 v55, v64
	v_mov_b32_e32 v64, v57
	v_mov_b32_e32 v56, v70
	v_mov_b32_e32 v57, v78
	v_mov_b32_e32 v78, v71
	v_mov_b32_e32 v70, v72
	v_mov_b32_e32 v71, v80
	v_mov_b32_e32 v80, v73
	v_mov_b32_e32 v72, v82
	v_mov_b32_e32 v73, v90
	v_mov_b32_e32 v90, v83
	v_mov_b32_e32 v82, v84
	v_mov_b32_e32 v83, v92
	v_mov_b32_e32 v92, v85
	v_mov_b32_e32 v84, v98
	v_mov_b32_e32 v85, v106
	v_mov_b32_e32 v106, v99
	v_mov_b32_e32 v98, v100
	v_mov_b32_e32 v99, v108
	v_mov_b32_e32 v108, v101
	v_mov_b32_e32 v100, v114
	v_pk_fma_f32 v[12:13], v[146:147], v[26:27], v[12:13] op_sel_hi:[0,1,1]
	v_pk_fma_f32 v[14:15], v[146:147], v[42:43], v[14:15] op_sel_hi:[0,1,1]
	v_pk_fma_f32 v[16:17], v[146:147], v[58:59], v[16:17] op_sel_hi:[0,1,1]
	v_pk_fma_f32 v[10:11], v[146:147], v[74:75], v[10:11] op_sel_hi:[0,1,1]
	v_pk_fma_f32 v[12:13], v[148:149], v[18:19], v[12:13] op_sel_hi:[0,1,1]
	v_pk_fma_f32 v[14:15], v[148:149], v[34:35], v[14:15] op_sel_hi:[0,1,1]
	v_pk_fma_f32 v[16:17], v[148:149], v[50:51], v[16:17] op_sel_hi:[0,1,1]
	v_pk_fma_f32 v[10:11], v[148:149], v[66:67], v[10:11] op_sel_hi:[0,1,1]
	v_pk_fma_f32 v[12:13], v[150:151], v[28:29], v[12:13] op_sel_hi:[0,1,1]
	v_pk_fma_f32 v[14:15], v[150:151], v[44:45], v[14:15] op_sel_hi:[0,1,1]
	v_pk_fma_f32 v[16:17], v[150:151], v[60:61], v[16:17] op_sel_hi:[0,1,1]
	v_pk_fma_f32 v[10:11], v[150:151], v[76:77], v[10:11] op_sel_hi:[0,1,1]
	v_pk_fma_f32 v[12:13], v[152:153], v[68:69], v[12:13] op_sel_hi:[0,1,1]
	v_pk_fma_f32 v[14:15], v[152:153], v[24:25], v[14:15] op_sel_hi:[0,1,1]
	v_pk_fma_f32 v[16:17], v[152:153], v[40:41], v[16:17] op_sel_hi:[0,1,1]
	v_pk_fma_f32 v[10:11], v[152:153], v[56:57], v[10:11] op_sel_hi:[0,1,1]
	v_pk_fma_f32 v[12:13], v[154:155], v[30:31], v[12:13] op_sel_hi:[0,1,1]
	v_pk_fma_f32 v[14:15], v[154:155], v[46:47], v[14:15] op_sel_hi:[0,1,1]
	v_pk_fma_f32 v[16:17], v[154:155], v[62:63], v[16:17] op_sel_hi:[0,1,1]
	v_pk_fma_f32 v[10:11], v[154:155], v[78:79], v[10:11] op_sel_hi:[0,1,1]
	v_pk_fma_f32 v[12:13], v[156:157], v[22:23], v[12:13] op_sel_hi:[0,1,1]
	v_pk_fma_f32 v[14:15], v[156:157], v[38:39], v[14:15] op_sel_hi:[0,1,1]
	v_pk_fma_f32 v[16:17], v[156:157], v[54:55], v[16:17] op_sel_hi:[0,1,1]
	v_pk_fma_f32 v[10:11], v[156:157], v[70:71], v[10:11] op_sel_hi:[0,1,1]
	v_mov_b32_e32 v101, v122
	v_mov_b32_e32 v122, v115
	v_mov_b32_e32 v114, v116
	v_mov_b32_e32 v115, v124
	v_mov_b32_e32 v124, v117
	v_mov_b32_e32 v116, v130
	v_mov_b32_e32 v117, v138
	v_pk_fma_f32 v[12:13], v[158:159], v[32:33], v[12:13] op_sel_hi:[0,1,1]
	v_pk_fma_f32 v[14:15], v[158:159], v[48:49], v[14:15] op_sel_hi:[0,1,1]
	v_pk_fma_f32 v[16:17], v[158:159], v[64:65], v[16:17] op_sel_hi:[0,1,1]
	v_pk_fma_f32 v[10:11], v[158:159], v[80:81], v[10:11] op_sel_hi:[0,1,1]
	v_mov_b32_e32 v138, v131
	v_pk_fma_f32 v[12:13], v[160:161], v[72:73], v[12:13] op_sel_hi:[0,1,1]
	v_pk_fma_f32 v[14:15], v[160:161], v[84:85], v[14:15] op_sel_hi:[0,1,1]
	v_pk_fma_f32 v[16:17], v[160:161], v[100:101], v[16:17] op_sel_hi:[0,1,1]
	v_pk_fma_f32 v[10:11], v[160:161], v[116:117], v[10:11] op_sel_hi:[0,1,1]
	v_mov_b32_e32 v130, v132
	v_mov_b32_e32 v131, v140
	v_pk_fma_f32 v[12:13], v[162:163], v[90:91], v[12:13] op_sel_hi:[0,1,1]
; #define LDS_BARRIER() do { asm volatile("s_waitcnt lgkmcnt(0)" ::: "memory"); __builtin_amdgcn_s_barrier(); asm volatile("" ::: "memory"); } while (0)
; __device__ __forceinline__ void phase_mod(const float* c, const float* ada_w, const float* ada_b, float* mod, unsigned char* ldsb) {
;     ...
; #pragma unroll 16
;         for (int k = k0; k < k0 + 128; ++k) {
;             const float wv = W[(unsigned)k * 9216];
; #pragma unroll
;             for (int b = 0; b < 8; ++b) acc[b] += cact[b * 1024 + k] * wv;
;         }
; #pragma unroll
;         for (int b = 0; b < 8; ++b) red[(w * 8 + b) * 64 + lane] = acc[b];
;         LDS_BARRIER();
;         {
;             const int b = w;
;             float s = ada_b[l * 9216 + n0 + lane];
; #pragma unroll
;             for (int ww = 0; ww < 8; ++ww) s += red[(ww * 8 + b) * 64 + lane];
;             mod[(unsigned)(l * 8 + b) * 9216 + n0 + lane] = s;
;         }
;         LDS_BARRIER();
	v_pk_fma_f32 v[14:15], v[162:163], v[106:107], v[14:15] op_sel_hi:[0,1,1]
	v_pk_fma_f32 v[16:17], v[162:163], v[122:123], v[16:17] op_sel_hi:[0,1,1]
	v_pk_fma_f32 v[10:11], v[162:163], v[138:139], v[10:11] op_sel_hi:[0,1,1]
	v_mov_b32_e32 v140, v133
	v_pk_fma_f32 v[12:13], v[164:165], v[82:83], v[12:13] op_sel_hi:[0,1,1]
	v_pk_fma_f32 v[14:15], v[164:165], v[98:99], v[14:15] op_sel_hi:[0,1,1]
	v_pk_fma_f32 v[16:17], v[164:165], v[114:115], v[16:17] op_sel_hi:[0,1,1]
	v_pk_fma_f32 v[10:11], v[164:165], v[130:131], v[10:11] op_sel_hi:[0,1,1]
	v_mov_b32_e32 v132, v86
	v_mov_b32_e32 v133, v94
	v_mov_b32_e32 v94, v87
	v_mov_b32_e32 v86, v88
	v_mov_b32_e32 v87, v96
	v_mov_b32_e32 v96, v89
	v_mov_b32_e32 v88, v102
	v_mov_b32_e32 v89, v110
	v_mov_b32_e32 v110, v103
	v_mov_b32_e32 v102, v104
	v_mov_b32_e32 v103, v112
	v_mov_b32_e32 v112, v105
	v_mov_b32_e32 v104, v118
	v_mov_b32_e32 v105, v126
	v_mov_b32_e32 v126, v119
	v_mov_b32_e32 v118, v120
	v_mov_b32_e32 v119, v128
	v_mov_b32_e32 v128, v121
	v_mov_b32_e32 v120, v134
	v_mov_b32_e32 v121, v142
	v_pk_fma_f32 v[12:13], v[166:167], v[92:93], v[12:13] op_sel_hi:[0,1,1]
	v_pk_fma_f32 v[14:15], v[166:167], v[108:109], v[14:15] op_sel_hi:[0,1,1]
	v_pk_fma_f32 v[16:17], v[166:167], v[124:125], v[16:17] op_sel_hi:[0,1,1]
	v_pk_fma_f32 v[10:11], v[166:167], v[140:141], v[10:11] op_sel_hi:[0,1,1]
	v_mov_b32_e32 v142, v135
	v_pk_fma_f32 v[12:13], v[168:169], v[132:133], v[12:13] op_sel_hi:[0,1,1]
	v_pk_fma_f32 v[14:15], v[168:169], v[88:89], v[14:15] op_sel_hi:[0,1,1]
	v_pk_fma_f32 v[16:17], v[168:169], v[104:105], v[16:17] op_sel_hi:[0,1,1]
	v_pk_fma_f32 v[10:11], v[168:169], v[120:121], v[10:11] op_sel_hi:[0,1,1]
	v_mov_b32_e32 v134, v136
	v_mov_b32_e32 v135, v144
	v_pk_fma_f32 v[12:13], v[170:171], v[94:95], v[12:13] op_sel_hi:[0,1,1]
	v_pk_fma_f32 v[14:15], v[170:171], v[110:111], v[14:15] op_sel_hi:[0,1,1]
	v_pk_fma_f32 v[16:17], v[170:171], v[126:127], v[16:17] op_sel_hi:[0,1,1]
	v_pk_fma_f32 v[10:11], v[170:171], v[142:143], v[10:11] op_sel_hi:[0,1,1]
	s_add_i32 s77, s77, 0x24000
	s_add_i32 s9, s9, 64
	v_mov_b32_e32 v144, v137
	v_pk_fma_f32 v[12:13], v[172:173], v[86:87], v[12:13] op_sel_hi:[0,1,1]
	v_pk_fma_f32 v[14:15], v[172:173], v[102:103], v[14:15] op_sel_hi:[0,1,1]
	v_pk_fma_f32 v[16:17], v[172:173], v[118:119], v[16:17] op_sel_hi:[0,1,1]
	v_pk_fma_f32 v[10:11], v[172:173], v[134:135], v[10:11] op_sel_hi:[0,1,1]
	s_cmp_eq_u32 s77, 0x120000
	v_pk_fma_f32 v[12:13], v[174:175], v[96:97], v[12:13] op_sel_hi:[0,1,1]
	v_pk_fma_f32 v[14:15], v[174:175], v[112:113], v[14:15] op_sel_hi:[0,1,1]
	v_pk_fma_f32 v[16:17], v[174:175], v[128:129], v[16:17] op_sel_hi:[0,1,1]
	v_pk_fma_f32 v[10:11], v[174:175], v[144:145], v[10:11] op_sel_hi:[0,1,1]
	s_cbranch_scc0 .LBB0_9
	s_mul_i32 s6, s76, 0x2400
	s_add_i32 s6, s6, s8
	v_add_u32_e32 v4, s72, v1
	v_or_b32_e32 v8, s6, v2
	v_readlane_b32 s56, v253, 16
	ds_write2st64_b32 v4, v12, v13 offset0:128 offset1:129
	ds_write2st64_b32 v4, v14, v15 offset0:130 offset1:131
	ds_write2st64_b32 v4, v16, v17 offset0:132 offset1:133
	ds_write2st64_b32 v4, v10, v11 offset0:134 offset1:135
	v_ashrrev_i32_e32 v9, 31, v8
	v_readlane_b32 s62, v253, 22
	v_readlane_b32 s63, v253, 23
	s_waitcnt lgkmcnt(0)
	s_barrier
	s_lshl_b32 s6, s76, 3
	v_lshl_add_u64 v[8:9], v[8:9], 2, s[62:63]
	global_load_dword v18, v[8:9], off
	s_add_i32 s6, s6, s33
	s_mulk_i32 s6, 0x2400
	ds_read2st64_b32 v[8:9], v3 offset0:128 offset1:136
	ds_read2st64_b32 v[10:11], v3 offset0:144 offset1:152
	ds_read2st64_b32 v[12:13], v3 offset0:160 offset1:168
	ds_read2st64_b32 v[14:15], v3 offset0:176 offset1:184
	s_add_i32 s6, s6, s8
	v_or_b32_e32 v4, s6, v2
	v_lshl_add_u64 v[16:17], v[4:5], 2, s[0:1]
	s_add_i32 s3, s3, s34
	v_readlane_b32 s57, v253, 17
	v_readlane_b32 s60, v253, 20
	v_readlane_b32 s61, v253, 21
	v_readlane_b32 s70, v253, 30
	v_readlane_b32 s71, v253, 31
	s_cmpk_gt_i32 s3, 0x11f
	v_readlane_b32 s58, v253, 18
	v_readlane_b32 s59, v253, 19
	v_readlane_b32 s64, v253, 24
	v_readlane_b32 s65, v253, 25
	v_readlane_b32 s66, v253, 26
	v_readlane_b32 s67, v253, 27
	v_readlane_b32 s68, v253, 28
	v_readlane_b32 s69, v253, 29
	s_waitcnt vmcnt(0) lgkmcnt(3)
	v_add_f32_e32 v4, v18, v8
	v_add_f32_e32 v4, v4, v9
	s_waitcnt lgkmcnt(2)
	v_add_f32_e32 v4, v4, v10
	v_add_f32_e32 v4, v4, v11
	s_waitcnt lgkmcnt(1)
	v_add_f32_e32 v4, v4, v12
	v_add_f32_e32 v4, v4, v13
	s_waitcnt lgkmcnt(0)
	v_add_f32_e32 v4, v4, v14
	v_add_f32_e32 v4, v4, v15
	global_store_dword v[16:17], v4, off
	s_waitcnt lgkmcnt(0)
	s_barrier
	s_cbranch_scc0 .LBB0_8
